# P7 row-stat exchange: dropped the L1 invalidate (slots are read with sc1 loads)
# speedup vs baseline: 1.0912x; 1.0064x over previous
;     __device__ __forceinline__ void fused(f32x4 (&acc)[2][2][4][2], const Unit& u, int wr, int wc, int fr, int fq, PG8_LAS unsigned char* lds, int wid, int lane) const {
;     ...
;         if (tid == 0) {
;             unsigned* cw = cnt + 64 * u.pm;
;             __hip_atomic_fetch_add(cw, 1u, __ATOMIC_RELAXED, __HIP_MEMORY_SCOPE_AGENT);
;             unsigned sp = 0;
;             while (__hip_atomic_load(cw, __ATOMIC_RELAXED, __HIP_MEMORY_SCOPE_AGENT) < 4u) { __builtin_amdgcn_s_sleep(2); if (++sp > (1u << 20)) break; }
;             __builtin_amdgcn_fence(__ATOMIC_ACQUIRE, "agent");
;         }
;         asm volatile("s_waitcnt vmcnt(0) lgkmcnt(0)" ::: "memory"); __builtin_amdgcn_s_barrier(); asm volatile("" ::: "memory");
;         if (tid < 256) {
;             const float* slot = xbuf + (size_t)(u.pm * BM + tid) * 4;
;             const float t = (__hip_atomic_load(slot, __ATOMIC_RELAXED, __HIP_MEMORY_SCOPE_AGENT) + __hip_atomic_load(slot + 1, __ATOMIC_RELAXED, __HIP_MEMORY_SCOPE_AGENT))
;                           + (__hip_atomic_load(slot + 2, __ATOMIC_RELAXED, __HIP_MEMORY_SCOPE_AGENT) + __hip_atomic_load(slot + 3, __ATOMIC_RELAXED, __HIP_MEMORY_SCOPE_AGENT));
;             Sr[tid] = rsqrtf(t * (1.0f / DM) + EPS);
;         }
.LBB0_1098:
.LBB0_1099:
	s_or_b64 exec, exec, s[8:9]
	s_waitcnt vmcnt(0) lgkmcnt(0)
	s_barrier
	s_and_saveexec_b64 s[8:9], s[0:1]
	s_cbranch_execz .LBB0_1101
	v_lshl_add_u64 v[0:1], v[0:1], 4, s[4:5]
	global_load_dword v4, v[0:1], off sc1
	global_load_dword v6, v[0:1], off offset:4 sc1
	global_load_dword v5, v[0:1], off offset:8 sc1
	global_load_dword v7, v[0:1], off offset:12 sc1
	v_mov_b32_e32 v3, 0x358637bd
	s_mov_b32 s0, 0x800000
	s_waitcnt vmcnt(0)
	v_pk_add_f32 v[0:1], v[4:5], v[6:7]
	s_nop 0
	v_add_f32_e32 v0, v0, v1
	v_fmac_f32_e32 v3, 0x3a800000, v0
	v_mul_f32_e32 v0, 0x4b800000, v3
	v_cmp_gt_f32_e32 vcc, s0, v3
	v_lshl_add_u32 v1, v2, 2, 0
	v_add_u32_e32 v1, 0x21400, v1
	v_cndmask_b32_e32 v0, v3, v0, vcc
	v_rsq_f32_e32 v0, v0
	s_nop 0
	v_mul_f32_e32 v2, 0x45800000, v0
	v_cndmask_b32_e32 v0, v0, v2, vcc
	ds_write_b32 v1, v0
